# P0 x to bf16 row loop: 8 row loads issued together instead of serialized load-wait-store, input pointer load hoisted
# baseline (speedup 1.0000x reference)
; __device__ __forceinline__ float wave_sum(float v) {
; #pragma unroll
;     for (int o = 1; o < 64; o <<= 1) v += __shfl_xor(v, o);
;     return v; }
; __device__ __forceinline__ void p0_prologue(Frame& F) {
;     ...
;     { const int gw = F.bid * NWAVES + F.wave, NGW = F.G * NWAVES; bf16* xb = (bf16*)(F.ws + WS_XN); float* ssq = (float*)(F.ws + WS_SSQ);
;       for (int m = gw; m < MTOK; m += NGW) { const f32x4* xr = (const f32x4*)(F.in[0] + (size_t)m * D) + F.lane; v2u* o8 = (v2u*)(xb + (size_t)m * D) + F.lane; float sq = 0.f;
; #pragma unroll
;           for (int j = 0; j < 8; ++j) { const f32x4 v = xr[64 * j]; sq += (v.x * v.x + v.y * v.y) + (v.z * v.z + v.w * v.w); v2u w; w.x = pk2(v.x, v.y); w.y = pk2(v.z, v.w); o8[64 * j] = w; }
;           sq = wave_sum(sq); if (F.lane < 32) ssq[(size_t)m * 32 + F.lane] = (F.lane == 0) ? sq : 0.f; } }
.LBB0_50:
	s_cmpk_gt_i32 s10, 0x3fff
	s_cbranch_scc1 .LBB0_55
	v_mbcnt_lo_u32_b32 v2, -1, 0
	v_mbcnt_hi_u32_b32 v2, -1, v2
	v_and_b32_e32 v3, 64, v2
	v_add_u32_e32 v3, 64, v3
	v_xor_b32_e32 v4, 1, v2
	v_cmp_lt_i32_e32 vcc, v4, v3
	s_ashr_i32 s11, s10, 31
	s_lshl_b64 s[12:13], s[10:11], 7
	v_cndmask_b32_e32 v4, v2, v4, vcc
	v_lshlrev_b32_e32 v10, 2, v4
	v_xor_b32_e32 v4, 2, v2
	v_cmp_lt_i32_e32 vcc, v4, v3
	s_lshl_b64 s[14:15], s[10:11], 12
	s_lshl_b64 s[16:17], s[10:11], 13
	v_cndmask_b32_e32 v4, v2, v4, vcc
	v_lshlrev_b32_e32 v11, 2, v4
	v_xor_b32_e32 v4, 4, v2
	v_cmp_lt_i32_e32 vcc, v4, v3
	v_cmp_gt_u32_e64 s[4:5], 32, v1
	v_cmp_eq_u32_e64 s[6:7], 0, v1
	v_cndmask_b32_e32 v4, v2, v4, vcc
	v_lshlrev_b32_e32 v12, 2, v4
	v_xor_b32_e32 v4, 8, v2
	v_cmp_lt_i32_e32 vcc, v4, v3
	s_ashr_i32 s87, s86, 31
	v_mov_b32_e32 v5, s15
	v_cndmask_b32_e32 v4, v2, v4, vcc
	v_lshlrev_b32_e32 v13, 2, v4
	v_xor_b32_e32 v4, 16, v2
	v_cmp_lt_i32_e32 vcc, v4, v3
	v_mov_b32_e32 v7, s17
	v_mov_b64_e32 v[8:9], s[8:9]
	v_cndmask_b32_e32 v4, v2, v4, vcc
	v_lshlrev_b32_e32 v14, 2, v4
	v_xor_b32_e32 v4, 32, v2
	v_cmp_lt_i32_e32 vcc, v4, v3
	v_mov_b32_e32 v3, 0
	s_mov_b32 s11, 0x17300000
	v_cndmask_b32_e32 v2, v2, v4, vcc
	v_lshlrev_b32_e32 v15, 2, v2
	v_lshlrev_b32_e32 v2, 2, v1
	v_lshl_add_u64 v[2:3], s[12:13], 0, v[2:3]
	s_mov_b64 s[12:13], 0x3b700000
	v_lshl_or_b32 v4, v1, 3, s14
	v_lshl_or_b32 v1, v1, 4, s16
	v_lshl_add_u64 v[2:3], v[2:3], 0, s[12:13]
	s_lshl_b64 s[12:13], s[86:87], 7
	s_lshl_b64 s[14:15], s[86:87], 12
	v_or_b32_e32 v6, 0x1000, v1
	s_lshl_b64 s[16:17], s[86:87], 13
	s_movk_i32 s18, 0xf400
	s_movk_i32 s19, 0xf800
	s_movk_i32 s20, 0xfc00
	flat_load_dwordx2 v[68:69], v[8:9]
	s_waitcnt vmcnt(0) lgkmcnt(0)
	s_branch .LBB0_53

; __device__ __forceinline__ void p0_prologue(Frame& F) {
;     ...
;       for (int m = gw; m < MTOK; m += NGW) { const f32x4* xr = (const f32x4*)(F.in[0] + (size_t)m * D) + F.lane; v2u* o8 = (v2u*)(xb + (size_t)m * D) + F.lane; float sq = 0.f;
; #pragma unroll
;           for (int j = 0; j < 8; ++j) { const f32x4 v = xr[64 * j]; sq += (v.x * v.x + v.y * v.y) + (v.z * v.z + v.w * v.w); v2u w; w.x = pk2(v.x, v.y); w.y = pk2(v.z, v.w); o8[64 * j] = w; }
;           sq = wave_sum(sq); if (F.lane < 32) ssq[(size_t)m * 32 + F.lane] = (F.lane == 0) ? sq : 0.f; } }
.LBB0_53:
	s_waitcnt lgkmcnt(0)
	v_lshl_add_u64 v[20:21], s[0:1], 0, v[4:5]
	v_lshl_add_u64 v[44:45], v[68:69], 0, v[6:7]
	v_add_co_u32_e32 v16, vcc, 0xfffff000, v44
	s_nop 1
	v_addc_co_u32_e32 v17, vcc, -1, v45, vcc
	v_add_co_u32_e32 v48, vcc, s11, v20
	s_nop 1
	v_addc_co_u32_e32 v49, vcc, 0, v21, vcc
	v_add_co_u32_e32 v20, vcc, s18, v44
	s_nop 1
	v_addc_co_u32_e32 v21, vcc, -1, v45, vcc
	v_add_co_u32_e32 v24, vcc, s19, v44
	s_nop 1
	v_addc_co_u32_e32 v25, vcc, -1, v45, vcc
	v_add_co_u32_e32 v28, vcc, s20, v44
	s_nop 1
	v_addc_co_u32_e32 v29, vcc, -1, v45, vcc
	global_load_dwordx4 v[16:19], v[16:17], off
	global_load_dwordx4 v[20:23], v[20:21], off
	global_load_dwordx4 v[24:27], v[24:25], off
	global_load_dwordx4 v[28:31], v[28:29], off
	global_load_dwordx4 v[32:35], v[44:45], off
	global_load_dwordx4 v[36:39], v[44:45], off offset:1024
	global_load_dwordx4 v[40:43], v[44:45], off offset:2048
	global_load_dwordx4 v[44:47], v[44:45], off offset:3072
	s_waitcnt vmcnt(0)
	v_cvt_pk_bf16_f32 v52, v16, v17
	v_cvt_pk_bf16_f32 v53, v18, v19
	v_mul_f32_e32 v1, v17, v17
	v_mul_f32_e32 v50, v19, v19
	v_fmac_f32_e32 v1, v16, v16
	v_fmac_f32_e32 v50, v18, v18
	v_add_f32_e32 v1, v1, v50
	global_store_dwordx2 v[48:49], v[52:53], off
	v_cvt_pk_bf16_f32 v54, v20, v21
	v_cvt_pk_bf16_f32 v55, v22, v23
	v_mul_f32_e32 v50, v21, v21
	v_mul_f32_e32 v51, v23, v23
	v_fmac_f32_e32 v50, v20, v20
	v_fmac_f32_e32 v51, v22, v22
	v_add_f32_e32 v50, v50, v51
	v_add_f32_e32 v1, v1, v50
	global_store_dwordx2 v[48:49], v[54:55], off offset:512
	v_cvt_pk_bf16_f32 v56, v24, v25
	v_cvt_pk_bf16_f32 v57, v26, v27
	v_mul_f32_e32 v50, v25, v25
	v_mul_f32_e32 v51, v27, v27
	v_fmac_f32_e32 v50, v24, v24
	v_fmac_f32_e32 v51, v26, v26
	v_add_f32_e32 v50, v50, v51
	v_add_f32_e32 v1, v1, v50
	global_store_dwordx2 v[48:49], v[56:57], off offset:1024
	v_cvt_pk_bf16_f32 v58, v28, v29
	v_cvt_pk_bf16_f32 v59, v30, v31
	v_mul_f32_e32 v50, v29, v29
	v_mul_f32_e32 v51, v31, v31
	v_fmac_f32_e32 v50, v28, v28
	v_fmac_f32_e32 v51, v30, v30
	v_add_f32_e32 v50, v50, v51
	v_add_f32_e32 v1, v1, v50
	global_store_dwordx2 v[48:49], v[58:59], off offset:1536
	v_cvt_pk_bf16_f32 v60, v32, v33
	v_cvt_pk_bf16_f32 v61, v34, v35
	v_mul_f32_e32 v50, v33, v33
	v_mul_f32_e32 v51, v35, v35
	v_fmac_f32_e32 v50, v32, v32
	v_fmac_f32_e32 v51, v34, v34
	v_add_f32_e32 v50, v50, v51
	v_add_f32_e32 v1, v1, v50
	global_store_dwordx2 v[48:49], v[60:61], off offset:2048
	v_cvt_pk_bf16_f32 v62, v36, v37
	v_cvt_pk_bf16_f32 v63, v38, v39
	v_mul_f32_e32 v50, v37, v37
	v_mul_f32_e32 v51, v39, v39
	v_fmac_f32_e32 v50, v36, v36
	v_fmac_f32_e32 v51, v38, v38
	v_add_f32_e32 v50, v50, v51
	v_add_f32_e32 v1, v1, v50
	global_store_dwordx2 v[48:49], v[62:63], off offset:2560
	v_cvt_pk_bf16_f32 v64, v40, v41
	v_cvt_pk_bf16_f32 v65, v42, v43
	v_mul_f32_e32 v50, v41, v41
	v_mul_f32_e32 v51, v43, v43
	v_fmac_f32_e32 v50, v40, v40
	v_fmac_f32_e32 v51, v42, v42
	v_add_f32_e32 v50, v50, v51
	v_add_f32_e32 v1, v1, v50
	global_store_dwordx2 v[48:49], v[64:65], off offset:3072
	v_cvt_pk_bf16_f32 v66, v44, v45
	v_cvt_pk_bf16_f32 v67, v46, v47
	v_mul_f32_e32 v50, v45, v45
	v_mul_f32_e32 v51, v47, v47
	v_fmac_f32_e32 v50, v44, v44
	v_fmac_f32_e32 v51, v46, v46
	v_add_f32_e32 v50, v50, v51
	v_add_f32_e32 v1, v1, v50
	global_store_dwordx2 v[48:49], v[66:67], off offset:3584
	ds_bpermute_b32 v16, v10, v1
	s_waitcnt lgkmcnt(0)
	v_add_f32_e32 v1, v1, v16
	ds_bpermute_b32 v16, v11, v1
	s_waitcnt lgkmcnt(0)
	v_add_f32_e32 v1, v1, v16
	ds_bpermute_b32 v16, v12, v1
	s_waitcnt lgkmcnt(0)
	v_add_f32_e32 v1, v1, v16
	ds_bpermute_b32 v16, v13, v1
	s_waitcnt lgkmcnt(0)
	v_add_f32_e32 v1, v1, v16
	ds_bpermute_b32 v16, v14, v1
	s_waitcnt lgkmcnt(0)
	v_add_f32_e32 v1, v1, v16
	ds_bpermute_b32 v16, v15, v1
	s_and_saveexec_b64 s[8:9], s[4:5]
	s_cbranch_execz .LBB0_52
	s_waitcnt lgkmcnt(0)
	v_add_f32_e32 v1, v1, v16
	v_cndmask_b32_e64 v1, 0, v1, s[6:7]
	v_lshl_add_u64 v[16:17], s[0:1], 0, v[2:3]
	flat_store_dword v[16:17], v1
	s_branch .LBB0_52
